# placement guard also requires gridDim.x == 256 (local C->D barrier falls back to the global one otherwise)
# speedup vs baseline: 1.0002x; 1.0002x over previous
.LBB0_8:
	s_or_b64 exec, exec, s[4:5]
	s_waitcnt lgkmcnt(0)
	s_add_u32 s2, s86, 0x1000
	s_addc_u32 s3, s87, 0
	v_writelane_b32 v250, s2, 4
	s_barrier
	s_nop 0
	v_writelane_b32 v250, s3, 5
	s_getreg_b32 s2, hwreg(HW_REG_XCC_ID, 0, 4)
	s_and_b32 s2, s2, 15
	v_writelane_b32 v250, s2, 6
	v_cmp_eq_u32_e32 vcc, 0, v0
	s_and_saveexec_b64 s[2:3], vcc
	s_cbranch_execz .LBB0_11
	s_mov_b64 s[4:5], exec
	v_mbcnt_lo_u32_b32 v1, s4, 0
	v_mbcnt_hi_u32_b32 v1, s5, v1
	v_cmp_eq_u32_e32 vcc, 0, v1
	s_and_b64 s[6:7], exec, vcc
	s_mov_b64 exec, s[6:7]
	s_cbranch_execz .LBB0_11
	v_readlane_b32 s6, v250, 6
	s_bcnt1_i32_b64 s4, s[4:5]
	s_lshl_b32 s6, s6, 8
	v_mov_b32_e32 v2, s4
	v_readlane_b32 s4, v250, 4
	v_mov_b32_e32 v1, s6
	v_readlane_b32 s5, v250, 5
	s_nop 4
	global_atomic_add v1, v2, s[4:5] offset:1024
	v_readlane_b32 s6, v250, 6
	v_readlane_b32 s7, v250, 2
	s_and_b32 s7, s7, 7
	s_cmp_eq_u32 s6, s7
	s_cbranch_scc0 .Lxb_place_bad
	s_cmpk_eq_i32 s33, 0x100
	s_cbranch_scc1 .Lxb_place_ok
.Lxb_place_bad:
	v_mov_b32_e32 v1, 0x3400
	s_nop 0
	global_atomic_add v1, v2, s[4:5]
